# pc_phase item prologue: redundant s_waitcnt vmcnt(0) between the per-channel constant loads and the row loads removed (results first used after the second wait)
# baseline (speedup 1.0000x reference)
; __device__ __forceinline__ void pc_phase(LAS unsigned char* lds, const bf16* Pp_, const bf16* LO, const float* mu, const float* w0, const float* a0, const float* k_k, const float* k_a, const float* r_k, ...
;     ...
;         const int bh = item >> 8, c = item & 255, b = bh >> 4, h = bh & 15, ch = h * 64 + lane; const int m0 = b * SEQ + c * 16;
;         const float mu_r = mu[ch], mu_k = mu[1024 + ch], mu_v = mu[2048 + ch], w0c = w0[ch], a0c = a0[ch], kkc = k_k[ch], kac = k_a[ch], rkc = r_k[ch];
;         unsigned short sr_[17], sk_[17], sv_[17], slw[16], sla[16];
;         { const bf16* pp = Pp_ + (size_t)(c > 0 ? m0 - 1 : m0) * EV_IN_P + 3072 + ch; sr_[0] = pp[0]; sk_[0] = pp[1024]; sv_[0] = pp[2048]; }
; #pragma unroll
;         for (int t = 0; t < 16; ++t) { const bf16* pr = Pp_ + (size_t)(m0 + t) * EV_IN_P + 3072 + ch; sr_[t + 1] = pr[0]; sk_[t + 1] = pr[1024]; sv_[t + 1] = pr[2048];
;             const bf16* lo = LO + (size_t)(m0 + t) * LORA_N + ch; slw[t] = lo[0]; sla[t] = lo[1024]; }
.LBB0_281:
	s_and_b32 s1, s11, 0xff
	s_bfe_u32 s0, s11, 0x40008
	s_and_b32 s2, s11, 0xfffff000
	s_lshl_b32 s4, s1, 4
	v_lshl_or_b32 v16, s0, 6, v185
	s_or_b32 s56, s4, s2
	v_readlane_b32 s4, v255, 13
	v_lshlrev_b32_e32 v96, 2, v16
	v_readlane_b32 s5, v255, 14
	s_add_i32 s6, s56, -1
	s_cmp_eq_u32 s1, 0
	v_lshl_add_u64 v[6:7], s[4:5], 0, v[96:97]
	v_add_co_u32_e32 v8, vcc, 0x1000, v6
	global_load_dword v10, v[6:7], off
	s_nop 0
	v_addc_co_u32_e32 v9, vcc, 0, v7, vcc
	global_load_dword v9, v[8:9], off
	v_add_co_u32_e32 v6, vcc, 0x2000, v6
	v_readlane_b32 s4, v255, 15
	s_nop 0
	v_addc_co_u32_e32 v7, vcc, 0, v7, vcc
	v_readlane_b32 s5, v255, 16
	global_load_dword v12, v[6:7], off
	s_cselect_b64 s[94:95], -1, 0
	v_lshl_add_u64 v[6:7], s[4:5], 0, v[96:97]
	v_readlane_b32 s4, v255, 20
	v_readlane_b32 s5, v255, 21
	global_load_dword v8, v[6:7], off
	v_readlane_b32 s8, v254, 63
	v_lshl_add_u64 v[6:7], s[4:5], 0, v[96:97]
	v_readlane_b32 s4, v255, 22
	v_readlane_b32 s5, v255, 23
	global_load_dword v15, v[6:7], off
	v_readlane_b32 s9, v255, 0
	v_lshl_add_u64 v[6:7], s[4:5], 0, v[96:97]
	v_readlane_b32 s4, v255, 24
	v_readlane_b32 s5, v255, 25
	global_load_dword v14, v[6:7], off
	s_nop 0
	v_lshl_add_u64 v[6:7], s[4:5], 0, v[96:97]
	v_readlane_b32 s4, v255, 26
	v_readlane_b32 s5, v255, 27
	global_load_dword v13, v[6:7], off
	s_nop 0
	v_lshl_add_u64 v[6:7], s[4:5], 0, v[96:97]
	s_and_b64 s[4:5], s[94:95], exec
	s_cselect_b32 s1, s2, s6
	s_mul_hi_i32 s2, s1, 0x3400
	s_mulk_i32 s1, 0x3400
	s_add_u32 s4, s8, s1
	s_addc_u32 s5, s9, s2
	v_lshlrev_b32_e32 v96, 1, v16
	v_lshl_add_u64 v[16:17], s[4:5], 0, v[96:97]
	v_readlane_b32 s4, v255, 1
	v_readlane_b32 s5, v255, 2
	s_mul_i32 s2, s56, 0x3400
	global_load_dword v11, v[6:7], off
	v_lshl_add_u64 v[6:7], s[4:5], 0, v[96:97]
	s_mul_hi_i32 s1, s56, 0x3400
	s_add_u32 s4, s8, s2
	s_addc_u32 s5, s9, s1
	s_or_b32 s86, s56, 1
	v_lshl_add_u64 v[20:21], s[4:5], 0, v[96:97]
	v_mad_i64_i32 v[140:141], s[4:5], s56, v226, v[6:7]
	s_mul_i32 s2, s86, 0x3400
	s_mul_hi_i32 s1, s86, 0x3400
	s_add_u32 s4, s8, s2
	s_addc_u32 s5, s9, s1
	v_lshl_add_u64 v[64:65], s[4:5], 0, v[96:97]
	v_add_co_u32_e32 v68, vcc, s55, v64
	s_mov_b64 s[6:7], 0x1800
	s_nop 0
	v_addc_co_u32_e32 v69, vcc, 0, v65, vcc
	v_lshl_add_u64 v[66:67], v[64:65], 0, s[6:7]
	v_add_co_u32_e32 v64, vcc, s13, v64
	s_or_b32 s34, s56, 2
	s_nop 0
	v_addc_co_u32_e32 v65, vcc, 0, v65, vcc
	global_load_ushort v132, v[140:141], off
	global_load_ushort v129, v[68:69], off offset:2048
	global_load_ushort v130, v[66:67], off offset:2048
	global_load_ushort v131, v[64:65], off offset:2048
	v_mad_i64_i32 v[64:65], s[4:5], s86, v226, v[6:7]
	s_mul_i32 s2, s34, 0x3400
	s_mul_hi_i32 s1, s34, 0x3400
	s_add_u32 s4, s8, s2
	s_addc_u32 s5, s9, s1
	global_load_ushort v127, v[64:65], off
	global_load_ushort v128, v[64:65], off offset:2048
	v_lshl_add_u64 v[64:65], s[4:5], 0, v[96:97]
	v_add_co_u32_e32 v68, vcc, s55, v64
	v_lshl_add_u64 v[66:67], v[64:65], 0, s[6:7]
	s_nop 0
	v_addc_co_u32_e32 v69, vcc, 0, v65, vcc
	v_add_co_u32_e32 v64, vcc, s13, v64
	s_or_b32 s40, s56, 3
	s_nop 0
	v_addc_co_u32_e32 v65, vcc, 0, v65, vcc
	global_load_ushort v124, v[68:69], off offset:2048
	global_load_ushort v125, v[66:67], off offset:2048
	global_load_ushort v126, v[64:65], off offset:2048
	v_mad_i64_i32 v[64:65], s[4:5], s34, v226, v[6:7]
	s_mul_i32 s2, s40, 0x3400
	s_mul_hi_i32 s1, s40, 0x3400
	s_add_u32 s4, s8, s2
	s_addc_u32 s5, s9, s1
	global_load_ushort v122, v[64:65], off
	global_load_ushort v123, v[64:65], off offset:2048
	v_lshl_add_u64 v[64:65], s[4:5], 0, v[96:97]
	v_add_co_u32_e32 v68, vcc, s55, v64
	v_lshl_add_u64 v[66:67], v[64:65], 0, s[6:7]
	s_nop 0
	v_addc_co_u32_e32 v69, vcc, 0, v65, vcc
	v_add_co_u32_e32 v64, vcc, s13, v64
	s_or_b32 s72, s56, 4
	s_nop 0
	v_addc_co_u32_e32 v65, vcc, 0, v65, vcc
	global_load_ushort v119, v[68:69], off offset:2048
	global_load_ushort v120, v[66:67], off offset:2048
	global_load_ushort v121, v[64:65], off offset:2048
	v_mad_i64_i32 v[64:65], s[4:5], s40, v226, v[6:7]
	s_mul_i32 s2, s72, 0x3400
	s_mul_hi_i32 s1, s72, 0x3400
	s_add_u32 s4, s8, s2
	s_addc_u32 s5, s9, s1
	global_load_ushort v117, v[64:65], off
	global_load_ushort v118, v[64:65], off offset:2048
	v_lshl_add_u64 v[64:65], s[4:5], 0, v[96:97]
	v_add_co_u32_e32 v68, vcc, s55, v64
	v_lshl_add_u64 v[66:67], v[64:65], 0, s[6:7]
	s_nop 0
	v_addc_co_u32_e32 v69, vcc, 0, v65, vcc
	v_add_co_u32_e32 v64, vcc, s13, v64
	s_or_b32 s68, s56, 5
	s_nop 0
	v_addc_co_u32_e32 v65, vcc, 0, v65, vcc
	global_load_ushort v114, v[68:69], off offset:2048
	global_load_ushort v115, v[66:67], off offset:2048
	global_load_ushort v116, v[64:65], off offset:2048
	v_mad_i64_i32 v[64:65], s[4:5], s72, v226, v[6:7]
	s_mul_i32 s2, s68, 0x3400
	s_mul_hi_i32 s1, s68, 0x3400
	s_add_u32 s4, s8, s2
	s_addc_u32 s5, s9, s1
	global_load_ushort v112, v[64:65], off
	global_load_ushort v113, v[64:65], off offset:2048
	v_lshl_add_u64 v[64:65], s[4:5], 0, v[96:97]
	v_add_co_u32_e32 v68, vcc, s55, v64
	v_lshl_add_u64 v[66:67], v[64:65], 0, s[6:7]
	s_nop 0
	v_addc_co_u32_e32 v69, vcc, 0, v65, vcc
	v_add_co_u32_e32 v64, vcc, s13, v64
	s_or_b32 s66, s56, 6
	s_nop 0
	v_addc_co_u32_e32 v65, vcc, 0, v65, vcc
	global_load_ushort v109, v[68:69], off offset:2048
	global_load_ushort v110, v[66:67], off offset:2048
	global_load_ushort v111, v[64:65], off offset:2048
	v_mad_i64_i32 v[64:65], s[4:5], s68, v226, v[6:7]
	s_mul_i32 s2, s66, 0x3400
	s_mul_hi_i32 s1, s66, 0x3400
	s_add_u32 s4, s8, s2
	s_addc_u32 s5, s9, s1
	global_load_ushort v107, v[64:65], off
	global_load_ushort v108, v[64:65], off offset:2048
	v_lshl_add_u64 v[64:65], s[4:5], 0, v[96:97]
; __device__ __forceinline__ void pc_phase(LAS unsigned char* lds, const bf16* Pp_, const bf16* LO, const float* mu, const float* w0, const float* a0, const float* k_k, const float* k_a, const float* r_k, ...
;     ...
;         for (int t = 0; t < 16; ++t) { const bf16* pr = Pp_ + (size_t)(m0 + t) * EV_IN_P + 3072 + ch; sr_[t + 1] = pr[0]; sk_[t + 1] = pr[1024]; sv_[t + 1] = pr[2048];
;             const bf16* lo = LO + (size_t)(m0 + t) * LORA_N + ch; slw[t] = lo[0]; sla[t] = lo[1024]; }
	v_add_co_u32_e32 v68, vcc, s55, v64
	v_lshl_add_u64 v[66:67], v[64:65], 0, s[6:7]
	s_nop 0
	v_addc_co_u32_e32 v69, vcc, 0, v65, vcc
	v_add_co_u32_e32 v64, vcc, s13, v64
	s_or_b32 s64, s56, 7
	s_nop 0
	v_addc_co_u32_e32 v65, vcc, 0, v65, vcc
	global_load_ushort v104, v[68:69], off offset:2048
	global_load_ushort v105, v[66:67], off offset:2048
	global_load_ushort v106, v[64:65], off offset:2048
	v_mad_i64_i32 v[64:65], s[4:5], s66, v226, v[6:7]
	s_mul_i32 s2, s64, 0x3400
	s_mul_hi_i32 s1, s64, 0x3400
	s_add_u32 s4, s8, s2
	s_addc_u32 s5, s9, s1
	global_load_ushort v102, v[64:65], off
	global_load_ushort v103, v[64:65], off offset:2048
	v_lshl_add_u64 v[64:65], s[4:5], 0, v[96:97]
	v_add_co_u32_e32 v68, vcc, s55, v64
	v_lshl_add_u64 v[66:67], v[64:65], 0, s[6:7]
	s_nop 0
	v_addc_co_u32_e32 v69, vcc, 0, v65, vcc
	v_add_co_u32_e32 v64, vcc, s13, v64
	s_or_b32 s62, s56, 8
	s_nop 0
	v_addc_co_u32_e32 v65, vcc, 0, v65, vcc
	global_load_ushort v99, v[68:69], off offset:2048
	global_load_ushort v100, v[66:67], off offset:2048
	global_load_ushort v101, v[64:65], off offset:2048
	v_mad_i64_i32 v[64:65], s[4:5], s64, v226, v[6:7]
	s_mul_i32 s2, s62, 0x3400
	s_mul_hi_i32 s1, s62, 0x3400
	s_add_u32 s4, s8, s2
	s_addc_u32 s5, s9, s1
	global_load_ushort v95, v[64:65], off
	global_load_ushort v98, v[64:65], off offset:2048
	v_lshl_add_u64 v[64:65], s[4:5], 0, v[96:97]
	v_add_co_u32_e32 v68, vcc, s55, v64
	v_lshl_add_u64 v[66:67], v[64:65], 0, s[6:7]
	s_nop 0
	v_addc_co_u32_e32 v69, vcc, 0, v65, vcc
	v_add_co_u32_e32 v64, vcc, s13, v64
	s_or_b32 s36, s56, 9
	s_nop 0
	v_addc_co_u32_e32 v65, vcc, 0, v65, vcc
	global_load_ushort v92, v[68:69], off offset:2048
	global_load_ushort v93, v[66:67], off offset:2048
	global_load_ushort v94, v[64:65], off offset:2048
	v_mad_i64_i32 v[64:65], s[4:5], s62, v226, v[6:7]
	s_mul_i32 s2, s36, 0x3400
	s_mul_hi_i32 s1, s36, 0x3400
	s_add_u32 s4, s8, s2
	s_addc_u32 s5, s9, s1
	global_load_ushort v90, v[64:65], off
	global_load_ushort v91, v[64:65], off offset:2048
	v_lshl_add_u64 v[64:65], s[4:5], 0, v[96:97]
	v_add_co_u32_e32 v68, vcc, s55, v64
	v_lshl_add_u64 v[66:67], v[64:65], 0, s[6:7]
	s_nop 0
	v_addc_co_u32_e32 v69, vcc, 0, v65, vcc
	v_add_co_u32_e32 v64, vcc, s13, v64
	s_or_b32 s84, s56, 10
	s_nop 0
	v_addc_co_u32_e32 v65, vcc, 0, v65, vcc
	global_load_ushort v87, v[68:69], off offset:2048
	global_load_ushort v88, v[66:67], off offset:2048
	global_load_ushort v89, v[64:65], off offset:2048
	v_mad_i64_i32 v[64:65], s[4:5], s36, v226, v[6:7]
	s_mul_i32 s2, s84, 0x3400
	s_mul_hi_i32 s1, s84, 0x3400
	s_add_u32 s4, s8, s2
	s_addc_u32 s5, s9, s1
	global_load_ushort v85, v[64:65], off
	global_load_ushort v86, v[64:65], off offset:2048
	v_lshl_add_u64 v[64:65], s[4:5], 0, v[96:97]
	v_add_co_u32_e32 v68, vcc, s55, v64
	v_lshl_add_u64 v[66:67], v[64:65], 0, s[6:7]
	s_nop 0
	v_addc_co_u32_e32 v69, vcc, 0, v65, vcc
	v_add_co_u32_e32 v64, vcc, s13, v64
	s_or_b32 s82, s56, 11
	s_nop 0
	v_addc_co_u32_e32 v65, vcc, 0, v65, vcc
	global_load_ushort v82, v[68:69], off offset:2048
	global_load_ushort v83, v[66:67], off offset:2048
	global_load_ushort v84, v[64:65], off offset:2048
	v_mad_i64_i32 v[64:65], s[4:5], s84, v226, v[6:7]
	s_mul_i32 s2, s82, 0x3400
	s_mul_hi_i32 s1, s82, 0x3400
	s_add_u32 s4, s8, s2
	s_addc_u32 s5, s9, s1
	global_load_ushort v80, v[64:65], off
	global_load_ushort v81, v[64:65], off offset:2048
	v_lshl_add_u64 v[64:65], s[4:5], 0, v[96:97]
	v_add_co_u32_e32 v68, vcc, s55, v64
	v_lshl_add_u64 v[66:67], v[64:65], 0, s[6:7]
	s_nop 0
	v_addc_co_u32_e32 v69, vcc, 0, v65, vcc
	v_add_co_u32_e32 v64, vcc, s13, v64
	s_or_b32 s80, s56, 12
	s_nop 0
	v_addc_co_u32_e32 v65, vcc, 0, v65, vcc
	global_load_ushort v77, v[68:69], off offset:2048
	global_load_ushort v78, v[66:67], off offset:2048
	global_load_ushort v79, v[64:65], off offset:2048
	v_mad_i64_i32 v[64:65], s[4:5], s82, v226, v[6:7]
	s_mul_i32 s2, s80, 0x3400
	s_mul_hi_i32 s1, s80, 0x3400
	s_add_u32 s4, s8, s2
	s_addc_u32 s5, s9, s1
	global_load_ushort v75, v[64:65], off
	global_load_ushort v76, v[64:65], off offset:2048
	v_lshl_add_u64 v[64:65], s[4:5], 0, v[96:97]
	v_add_co_u32_e32 v68, vcc, s55, v64
	v_lshl_add_u64 v[66:67], v[64:65], 0, s[6:7]
	s_nop 0
	v_addc_co_u32_e32 v69, vcc, 0, v65, vcc
	v_add_co_u32_e32 v64, vcc, s13, v64
	s_or_b32 s78, s56, 13
	s_nop 0
	v_addc_co_u32_e32 v65, vcc, 0, v65, vcc
	global_load_ushort v72, v[68:69], off offset:2048
	global_load_ushort v73, v[66:67], off offset:2048
	global_load_ushort v74, v[64:65], off offset:2048
	v_mad_i64_i32 v[64:65], s[4:5], s80, v226, v[6:7]
	s_mul_i32 s2, s78, 0x3400
	s_mul_hi_i32 s1, s78, 0x3400
	s_add_u32 s4, s8, s2
	s_addc_u32 s5, s9, s1
	global_load_ushort v70, v[64:65], off
	global_load_ushort v71, v[64:65], off offset:2048
	v_lshl_add_u64 v[64:65], s[4:5], 0, v[96:97]
	v_add_co_u32_e32 v66, vcc, s55, v64
	v_lshl_add_u64 v[68:69], v[64:65], 0, s[6:7]
	s_nop 0
	v_addc_co_u32_e32 v67, vcc, 0, v65, vcc
	v_add_co_u32_e32 v64, vcc, s13, v64
	global_load_ushort v66, v[66:67], off offset:2048
	s_nop 0
	global_load_ushort v67, v[68:69], off offset:2048
	v_addc_co_u32_e32 v65, vcc, 0, v65, vcc
; __device__ __forceinline__ float bf2f(bf16 b) { return __uint_as_float((unsigned)b << 16); }
; __device__ __forceinline__ bf16 f2bf(float f) { return (bf16)(pk_bf16(f, 0.f) & 0xffffu); }
; __device__ __forceinline__ float fexp(float x) { return __builtin_amdgcn_exp2f(x * 1.4426950408889634f); }
; __device__ __forceinline__ float flog(float x) { return __builtin_amdgcn_logf(x) * 0.6931471805599453f; }
; __device__ __forceinline__ float fsigmoid(float x) { return __builtin_amdgcn_rcpf(1.0f + fexp(-x)); }
; __device__ __forceinline__ void pc_phase(LAS unsigned char* lds, const bf16* Pp_, const bf16* LO, const float* mu, const float* w0, const float* a0, const float* k_k, const float* k_a, const float* r_k, ...
;     ...
;         for (int t = 0; t < 16; ++t) { const bf16* pr = Pp_ + (size_t)(m0 + t) * EV_IN_P + 3072 + ch; sr_[t + 1] = pr[0]; sk_[t + 1] = pr[1024]; sv_[t + 1] = pr[2048];
;             const bf16* lo = LO + (size_t)(m0 + t) * LORA_N + ch; slw[t] = lo[0]; sla[t] = lo[1024]; }
;         const float z1 = (c > 0) ? 1.0f : 0.0f;
;         float P = 1.0f, r1 = bf2f(sr_[0]) * z1, k1 = bf2f(sk_[0]) * z1, v1 = bf2f(sv_[0]) * z1;
; #pragma unroll
;         for (int t = 0; t < 16; ++t) {
;             const float r0 = bf2f(sr_[t + 1]), k0 = bf2f(sk_[t + 1]), v0 = bf2f(sv_[t + 1]);
;             const float r = r0 + (r1 - r0) * mu_r, k = k0 + (k1 - k0) * mu_k, v = v0 + (v1 - v0) * mu_v; r1 = r0; k1 = k0; v1 = v0;
;             const float z = -(w0c + bf2f(slw[t])); const float sp = fmaxf(z, 0.f) + flog(1.0f + fexp(-fabsf(z))); const float w = -sp - 0.5f;
;             const float dec = fexp(-fexp(w)); const float a = fsigmoid(a0c + bf2f(sla[t]));
;             float kk = k * kkc; const float n2 = wsum_dpp(kk * kk); kk = kk / fmaxf(sqrtf(n2), 1e-12f);
;             const float kp = bf2f(f2bf(k * (1.0f + (a - 1.0f) * kac))), bb = bf2f(f2bf(kk * a)), rr = bf2f(f2bf(r)); kk = bf2f(f2bf(kk));
;             const float coef = wsum_dpp(rr * kp * rkc);
;             SV[(ib + t) * 64 + lane] = f2bf(v);
;             if (lane == 0) COEF[(size_t)(m0 + t) * 16 + h] = coef;
;             const float Pp = P; P *= dec; const float inv = 1.0f / P;
;             XKK[t * 72 + lane] = f2bf(kk * Pp); XR[t * 72 + lane] = f2bf(rr * P); XK[t * 72 + lane] = f2bf(kp * inv); XB[t * 72 + lane] = f2bf(bb * inv); }
	global_load_ushort v68, v[64:65], off offset:2048
	v_add_co_u32_e32 v64, vcc, s55, v16
	v_lshl_add_u64 v[18:19], v[16:17], 0, s[6:7]
	s_nop 0
	v_addc_co_u32_e32 v65, vcc, 0, v17, vcc
	v_add_co_u32_e32 v16, vcc, s13, v16
	global_load_ushort v134, v[64:65], off offset:2048
	global_load_ushort v135, v[18:19], off offset:2048
	v_addc_co_u32_e32 v17, vcc, 0, v17, vcc
	global_load_ushort v138, v[16:17], off offset:2048
	v_add_co_u32_e32 v16, vcc, s55, v20
	v_lshl_add_u64 v[62:63], v[20:21], 0, s[6:7]
	s_nop 0
	v_addc_co_u32_e32 v17, vcc, 0, v21, vcc
	global_load_ushort v136, v[16:17], off offset:2048
	global_load_ushort v137, v[62:63], off offset:2048
	v_add_co_u32_e32 v16, vcc, s13, v20
	s_or_b32 s76, s56, 14
	s_nop 0
	v_addc_co_u32_e32 v17, vcc, 0, v21, vcc
	global_load_ushort v139, v[16:17], off offset:2048
	v_mad_i64_i32 v[16:17], s[4:5], s78, v226, v[6:7]
	global_load_ushort v65, v[16:17], off
	global_load_ushort v133, v[140:141], off offset:2048
	global_load_ushort v69, v[16:17], off offset:2048
	s_mul_i32 s2, s76, 0x3400
	s_mul_hi_i32 s1, s76, 0x3400
	s_add_u32 s4, s8, s2
	s_addc_u32 s5, s9, s1
	v_lshl_add_u64 v[16:17], s[4:5], 0, v[96:97]
	v_add_co_u32_e32 v20, vcc, s55, v16
	v_lshl_add_u64 v[18:19], v[16:17], 0, s[6:7]
	s_nop 0
	v_addc_co_u32_e32 v21, vcc, 0, v17, vcc
	v_add_co_u32_e32 v16, vcc, s13, v16
	s_or_b32 s74, s56, 15
	s_nop 0
	v_addc_co_u32_e32 v17, vcc, 0, v17, vcc
	global_load_ushort v62, v[20:21], off offset:2048
	global_load_ushort v63, v[18:19], off offset:2048
	global_load_ushort v64, v[16:17], off offset:2048
	v_mad_i64_i32 v[16:17], s[4:5], s76, v226, v[6:7]
	s_mul_i32 s2, s74, 0x3400
	s_mul_hi_i32 s1, s74, 0x3400
	s_add_u32 s4, s8, s2
	s_addc_u32 s5, s9, s1
	global_load_ushort v21, v[16:17], off
	global_load_ushort v61, v[16:17], off offset:2048
	v_lshl_add_u64 v[16:17], s[4:5], 0, v[96:97]
	v_add_co_u32_e32 v18, vcc, s55, v16
	v_lshl_add_u64 v[140:141], v[16:17], 0, s[6:7]
	s_nop 0
	v_addc_co_u32_e32 v19, vcc, 0, v17, vcc
	v_add_co_u32_e32 v16, vcc, s13, v16
	v_mad_i64_i32 v[6:7], s[4:5], s74, v226, v[6:7]
	s_nop 0
	v_addc_co_u32_e32 v17, vcc, 0, v17, vcc
	global_load_ushort v18, v[18:19], off offset:2048
	s_nop 0
	global_load_ushort v19, v[140:141], off offset:2048
	global_load_ushort v20, v[16:17], off offset:2048
	s_nop 0
	global_load_ushort v16, v[6:7], off
	global_load_ushort v17, v[6:7], off offset:2048
	v_cndmask_b32_e64 v96, 1.0, 0, s[94:95]
	s_lshl_b32 s0, s0, 2
	v_lshl_add_u64 v[6:7], s[88:89], 0, v[4:5]
	s_add_u32 s2, s49, s0
	s_addc_u32 s14, s35, 0
	s_waitcnt vmcnt(0) lgkmcnt(0)
	v_lshlrev_b32_e32 v140, 16, v134
	v_lshlrev_b32_e32 v141, 16, v135
	v_lshlrev_b32_e32 v138, 16, v138
	v_lshlrev_b32_e32 v136, 16, v136
	v_lshlrev_b32_e32 v135, 16, v137
	v_fma_f32 v137, v96, v140, -v136
	v_fma_f32 v137, v10, v137, v136
	v_cvt_pk_bf16_f32 v137, v137, s0
	v_lshlrev_b32_e32 v137, 16, v137
	v_lshlrev_b32_e32 v134, 16, v139
	v_fma_f32 v139, v96, v141, -v135
	v_lshlrev_b32_e32 v133, 16, v133
	v_add_f32_e32 v133, v15, v133
	v_mul_f32_e32 v133, 0xbfb8aa3b, v133
	v_exp_f32_e32 v133, v133
	v_fma_f32 v140, v9, v139, v135
	v_mul_f32_e32 v139, v14, v140
	v_fma_f32 v96, v96, v138, -v134
	v_add_f32_e32 v133, 1.0, v133
	v_rcp_f32_e32 v138, v133
	v_mul_f32_e32 v133, v139, v139
	v_fma_f32 v96, v12, v96, v134
	s_nop 0
	v_mov_b32_dpp v133, v133 quad_perm:[1,0,3,2] row_mask:0xf bank_mask:0xf bound_ctrl:1
	v_fmac_f32_e32 v133, v139, v139
	s_nop 1
	v_add_f32_dpp v133, v133, v133 quad_perm:[2,3,0,1] row_mask:0xf bank_mask:0xf bound_ctrl:1
	s_nop 1
	v_add_f32_dpp v133, v133, v133 row_ror:4 row_mask:0xf bank_mask:0xf bound_ctrl:1
	s_nop 1
	v_add_f32_dpp v133, v133, v133 row_ror:8 row_mask:0xf bank_mask:0xf bound_ctrl:1
	s_nop 0
	v_readlane_b32 s7, v133, 0
	v_readlane_b32 s8, v133, 16
	v_readlane_b32 s6, v133, 32
	v_readlane_b32 s9, v133, 48
	v_add_f32_e32 v133, -1.0, v138
	v_fma_f32 v133, v13, v133, 1.0
	v_mul_f32_e32 v133, v140, v133
	v_cvt_pk_bf16_f32 v133, v133, s0
	v_lshlrev_b32_e32 v133, 16, v133
	v_mul_f32_e32 v140, v137, v133
	v_mul_f32_e32 v141, v11, v140
	s_nop 1
	v_mov_b32_dpp v141, v141 quad_perm:[1,0,3,2] row_mask:0xf bank_mask:0xf bound_ctrl:1
	v_fmac_f32_e32 v141, v11, v140
	s_nop 1
	v_add_f32_dpp v140, v141, v141 quad_perm:[2,3,0,1] row_mask:0xf bank_mask:0xf bound_ctrl:1
	s_nop 1
	v_add_f32_dpp v140, v140, v140 row_ror:4 row_mask:0xf bank_mask:0xf bound_ctrl:1
	s_nop 1
	v_add_f32_dpp v140, v140, v140 row_ror:8 row_mask:0xf bank_mask:0xf bound_ctrl:1
	s_nop 0
	v_readlane_b32 s0, v140, 0
	v_readlane_b32 s15, v140, 16
	v_readlane_b32 s1, v140, 32
	v_readlane_b32 s17, v140, 48
	v_add_co_u32_e32 v140, vcc, 0x33600000, v6
	v_cvt_pk_bf16_f32 v96, v96, s0
	s_nop 0
	v_addc_co_u32_e32 v141, vcc, 0, v7, vcc
	global_store_short v[140:141], v96, off
	s_and_saveexec_b64 s[4:5], s[38:39]
	s_cbranch_execz .LBB0_283
	s_ashr_i32 s57, s56, 31
	s_lshl_b64 s[30:31], s[56:57], 6
	s_add_u32 s30, s2, s30
	v_mov_b32_e32 v140, s15
	v_mov_b32_e32 v141, s17
	s_addc_u32 s31, s14, s31
	v_pk_add_f32 v[140:141], s[0:1], v[140:141]
	s_nop 0
	v_add_f32_e32 v96, v140, v141
	v_mov_b64_e32 v[140:141], s[30:31]
	global_store_dword v[140:141], v96, off
